# lean11 = lean10 + attn_post item loads prefetched in the last m3 trip + dead m0 save/restore pairs removed in the attention phase
# baseline (speedup 1.0000x reference)
; #define LAS __attribute__((address_space(3)))
; #define LBAR() do { asm volatile("s_waitcnt lgkmcnt(0)" ::: "memory"); __builtin_amdgcn_s_barrier(); asm volatile("" ::: "memory"); } while (0)
; __device__ __forceinline__ void stage_conv_weights(const float* cw, const float* cb, LAS unsigned char* lds, int tid) {
;     LAS float* L = (LAS float*)(lds + CWL_OFF);
;     const float a0 = cw[tid], a1 = cw[tid + 512], a2 = cw[tid + 1024], a3 = cw[tid + 1536], b0 = cb[tid & 511];
;     L[tid] = a0; L[tid + 512] = a1; L[tid + 1024] = a2; L[tid + 1536] = a3; L[2048 + (tid & 511)] = b0;
;     LBAR();
; __device__ __forceinline__ void attn_post(const u16* O, u16* YC, const float* dlam, const float* dnorm, float lambda_init, int gt, int nthreads, int lane) {
;     ...
;     for (int item0 = gt >> 4; item0 < MH * 4; item0 += 8 * stride) {
;         v4u ra[8], rb[8];
; #pragma unroll
;         for (int q = 0; q < 8; ++q) { const int item = item0 + q * stride < MH * 4 ? item0 + q * stride : item0; const int row = item >> 2, hh = item & 3;
;             ra[q] = *(const v4u*)(O + (size_t)row * 1024 + (2 * hh) * 128 + sub * 8); rb[q] = *(const v4u*)(O + (size_t)row * 1024 + (2 * hh + 1) * 128 + sub * 8); }
.LBB0_952:
	s_and_b64 vcc, exec, s[0:1]
	s_cbranch_vccz .LBB0_997
	v_mov_b32_e32 v104, v230
	v_mov_b32_e32 v0, 0x21048
	ds_read_b64 v[0:1], v0
	v_mov_b32_e32 v2, 0x21050
	s_lshl_b32 s30, s78, 11
	ds_read_b64 v[2:3], v2
	s_lshl_b64 s[0:1], s[30:31], 2
	s_waitcnt lgkmcnt(0)
	v_readfirstlane_b32 s3, v0
	v_readfirstlane_b32 s2, v1
	s_add_u32 s0, s3, s0
	s_addc_u32 s1, s2, s1
	v_ashrrev_i32_e32 v105, 31, v104
	v_lshl_add_u64 v[0:1], v[104:105], 2, s[0:1]
	v_readfirstlane_b32 s5, v2
	s_lshl_b32 s30, s78, 9
	v_add_co_u32_e32 v2, vcc, s85, v0
	v_readfirstlane_b32 s4, v3
	s_lshl_b64 s[2:3], s[30:31], 2
	v_addc_co_u32_e32 v3, vcc, 0, v1, vcc
	s_add_u32 s2, s5, s2
	global_load_dword v4, v[0:1], off
	s_nop 0
	global_load_dword v0, v[0:1], off offset:2048
	s_nop 0
	global_load_dword v1, v[2:3], off
	s_nop 0
	global_load_dword v2, v[2:3], off offset:2048
	v_lshlrev_b32_e32 v3, 2, v104
	s_addc_u32 s3, s4, s3
	v_and_b32_e32 v5, 0x7fc, v3
	global_load_dword v6, v5, s[2:3]
	v_readlane_b32 s0, v255, 6
	s_cmpk_lt_i32 s58, 0x400
	v_and_b32_e32 v105, 63, v104
	v_add_u32_e32 v3, s0, v3
	v_add_u32_e32 v5, s0, v5
	s_mov_b64 s[0:1], -1
	s_waitcnt vmcnt(0)
	ds_write2st64_b32 v3, v4, v0 offset1:8
	ds_write2st64_b32 v3, v1, v2 offset0:16 offset1:24
	ds_write_b32 v5, v6 offset:8192
	s_waitcnt lgkmcnt(0)
	s_barrier
	s_cbranch_scc1 .LBB0_955
	s_lshl_b32 s30, s78, 8
	v_and_b32_e32 v220, 63, v104
	s_mov_b64 s[0:1], 0
	s_mov_b64 s[70:71], s[30:31]
	v_lshrrev_b32_e32 v210, 6, v104
	v_lshlrev_b32_e32 v210, 11, v210
	v_bfe_u32 v211, v104, 4, 2
	v_lshl_add_u32 v210, v211, 9, v210
	v_and_b32_e32 v211, 15, v104
	v_lshl_add_u32 v210, v211, 4, v210
	s_add_u32 s64, s62, 0x15400000
	s_addc_u32 s65, s63, 0
	s_lshl_b32 s91, s58, 14
	s_add_u32 s64, s64, s91
	s_addc_u32 s65, s65, 0
	global_load_dwordx4 v[146:149], v210, s[64:65]
	global_load_dwordx4 v[150:153], v210, s[64:65] offset:256
	s_add_u32 s64, s64, 0x400000
	s_addc_u32 s65, s65, 0
	global_load_dwordx4 v[154:157], v210, s[64:65]
	global_load_dwordx4 v[158:161], v210, s[64:65] offset:256
	s_add_u32 s64, s64, 0x400000
	s_addc_u32 s65, s65, 0
	global_load_dwordx4 v[162:165], v210, s[64:65]
	global_load_dwordx4 v[166:169], v210, s[64:65] offset:256
	s_add_u32 s64, s64, 0x400000
	s_addc_u32 s65, s65, 0
	global_load_dwordx4 v[170:173], v210, s[64:65]
	global_load_dwordx4 v[174:177], v210, s[64:65] offset:256
	s_add_u32 s64, s64, 0x400000
	s_addc_u32 s65, s65, 0
	global_load_dwordx4 v[178:181], v210, s[64:65]
	global_load_dwordx4 v[182:185], v210, s[64:65] offset:256
	s_add_u32 s64, s64, 0x400000
	s_addc_u32 s65, s65, 0
	global_load_dwordx4 v[186:189], v210, s[64:65]
	global_load_dwordx4 v[190:193], v210, s[64:65] offset:256
	s_add_u32 s64, s64, 0x400000
	s_addc_u32 s65, s65, 0
	global_load_dwordx4 v[194:197], v210, s[64:65]
	global_load_dwordx4 v[198:201], v210, s[64:65] offset:256
	s_add_u32 s64, s64, 0x400000
	s_addc_u32 s65, s65, 0
	global_load_dwordx4 v[202:205], v210, s[64:65]
	global_load_dwordx4 v[206:209], v210, s[64:65] offset:256

; #define LAS __attribute__((address_space(3)))
; __device__ __forceinline__ void unpack8(const v4u r, float* x) { x[0] = bflo(r.x); x[1] = bfhi(r.x); x[2] = bflo(r.y); x[3] = bfhi(r.y); x[4] = bflo(r.z); x[5] = bfhi(r.z); x[6] = bflo(r.w); x[7] = bfhi(r.w); }
; __device__ __forceinline__ float siluf_(float x) { return x * __builtin_amdgcn_rcpf(1.0f + __builtin_amdgcn_exp2f(-1.4426950408889634f * x)); }
; __device__ __forceinline__ void conv8r(const v4u* rows, const LAS float* cwL, int ch0, float* o, int tpos) {
; #pragma unroll
;     for (int i = 0; i < 8; ++i) o[i] = cwL[2048 + ch0 + i];
; #pragma unroll
;     for (int j = 0; j < 4; ++j) { float x[8]; unpack8(rows[j], x); const float keep = tpos - 3 + j >= 0 ? 1.0f : 0.0f;
; #pragma unroll
;         for (int i = 0; i < 8; ++i) o[i] += cwL[j * 512 + ch0 + i] * (x[i] * keep); }
; #pragma unroll
;     for (int i = 0; i < 8; ++i) o[i] = siluf_(o[i]);
; }
; __device__ __forceinline__ void m3_compute(const M3In& I, const float* mnorm, u16* YB, LAS unsigned char* lds, int un, int tid) {
;     ...
;     { float q[8], k[8], v[8];
;         conv8r(I.q, cwL, h * 64 + dg * 8, q, c * 64 + s);
;         conv8r(I.k, cwL, 256 + h * 64 + dg * 8, k, c * 64 + s);
; #pragma unroll
;         for (int i = 0; i < 8; ++i) k[i] *= 0.125f;
.LBB0_960:
	s_or_b64 exec, exec, s[76:77]
	s_and_b32 s50, s37, 0xfc0
	s_and_b32 s30, s22, 0xc0
	s_waitcnt vmcnt(16)
	v_add_u32_e32 v88, s50, v109
	v_or_b32_e32 v140, s30, v119
	v_cmp_lt_i32_e32 vcc, 2, v88
	s_waitcnt vmcnt(15)
	s_cmp_eq_u64 s[74:75], 0
	s_cbranch_scc1 .Lk5a_nopf
	v_lshrrev_b32_e32 v210, 6, v104
	v_lshlrev_b32_e32 v210, 11, v210
	v_bfe_u32 v211, v104, 4, 2
	v_lshl_add_u32 v210, v211, 9, v210
	v_and_b32_e32 v211, 15, v104
	v_lshl_add_u32 v210, v211, 4, v210
	s_add_u32 s64, s62, 0x15400000
	s_addc_u32 s65, s63, 0
	s_lshl_b32 s91, s58, 14
	s_add_u32 s64, s64, s91
	s_addc_u32 s65, s65, 0
	global_load_dwordx4 v[146:149], v210, s[64:65]
	global_load_dwordx4 v[150:153], v210, s[64:65] offset:256
	s_add_u32 s64, s64, 0x400000
	s_addc_u32 s65, s65, 0
	global_load_dwordx4 v[154:157], v210, s[64:65]
	global_load_dwordx4 v[158:161], v210, s[64:65] offset:256
	s_add_u32 s64, s64, 0x400000
	s_addc_u32 s65, s65, 0
	global_load_dwordx4 v[162:165], v210, s[64:65]
	global_load_dwordx4 v[166:169], v210, s[64:65] offset:256
	s_add_u32 s64, s64, 0x400000
	s_addc_u32 s65, s65, 0
	global_load_dwordx4 v[170:173], v210, s[64:65]
	global_load_dwordx4 v[174:177], v210, s[64:65] offset:256
	s_add_u32 s64, s64, 0x400000
	s_addc_u32 s65, s65, 0
	global_load_dwordx4 v[178:181], v210, s[64:65]
	global_load_dwordx4 v[182:185], v210, s[64:65] offset:256
	s_add_u32 s64, s64, 0x400000
	s_addc_u32 s65, s65, 0
	global_load_dwordx4 v[186:189], v210, s[64:65]
	global_load_dwordx4 v[190:193], v210, s[64:65] offset:256
	s_add_u32 s64, s64, 0x400000
	s_addc_u32 s65, s65, 0
	global_load_dwordx4 v[194:197], v210, s[64:65]
	global_load_dwordx4 v[198:201], v210, s[64:65] offset:256
	s_add_u32 s64, s64, 0x400000
	s_addc_u32 s65, s65, 0
	global_load_dwordx4 v[202:205], v210, s[64:65]
	global_load_dwordx4 v[206:209], v210, s[64:65] offset:256
.Lk5a_nopf:
	v_lshl_add_u32 v89, v140, 2, 0
	v_add_u32_e32 v141, 0x19000, v89
	v_cndmask_b32_e64 v122, 0, 1.0, vcc
	v_cmp_lt_i32_e32 vcc, 1, v88
	ds_read_b128 v[92:95], v141 offset:1024
	ds_read_b128 v[100:103], v141 offset:5120
	v_cndmask_b32_e64 v120, 0, 1.0, vcc
	v_cmp_lt_i32_e32 vcc, 0, v88
	v_lshlrev_b32_e32 v96, 16, v84
	v_and_b32_e32 v97, 0xffff0000, v84
	v_cndmask_b32_e64 v118, 0, 1.0, vcc
	v_cmp_lt_i32_e32 vcc, -1, v88
	ds_read_b128 v[88:91], v141 offset:9216
	v_pk_mul_f32 v[96:97], v[122:123], v[96:97] op_sel_hi:[0,1]
	ds_read_b128 v[142:145], v141 offset:7168
	v_cndmask_b32_e64 v116, 0, 1.0, vcc
	v_lshlrev_b32_e32 v84, 16, v85
	s_waitcnt lgkmcnt(1)
	v_pk_fma_f32 v[88:89], v[96:97], v[92:93], v[88:89]
	ds_read_b128 v[96:99], v141 offset:3072
	v_lshlrev_b32_e32 v92, 16, v80
	v_and_b32_e32 v93, 0xffff0000, v80
	v_pk_mul_f32 v[92:93], v[120:121], v[92:93] op_sel_hi:[0,1]
	v_and_b32_e32 v85, 0xffff0000, v85
	s_waitcnt lgkmcnt(0)
	v_pk_fma_f32 v[88:89], v[92:93], v[96:97], v[88:89]
	v_lshlrev_b32_e32 v92, 16, v76
	v_and_b32_e32 v93, 0xffff0000, v76
	v_pk_mul_f32 v[92:93], v[118:119], v[92:93] op_sel_hi:[0,1]
	v_pk_fma_f32 v[88:89], v[92:93], v[100:101], v[88:89]
	v_lshlrev_b32_e32 v92, 16, v72
	v_and_b32_e32 v93, 0xffff0000, v72
	v_pk_mul_f32 v[92:93], v[116:117], v[92:93] op_sel_hi:[0,1]
	v_pk_fma_f32 v[88:89], v[92:93], v[142:143], v[88:89]
	v_pk_mul_f32 v[84:85], v[122:123], v[84:85] op_sel_hi:[0,1]
	v_mul_f32_e32 v72, 0xbfb8aa3b, v88
	v_exp_f32_e32 v72, v72
	v_lshlrev_b32_e32 v80, 16, v81
	v_and_b32_e32 v81, 0xffff0000, v81
	v_pk_fma_f32 v[84:85], v[84:85], v[94:95], v[90:91]
	v_add_f32_e32 v72, 1.0, v72
	v_rcp_f32_e32 v92, v72
	v_mul_f32_e32 v72, 0xbfb8aa3b, v89
	v_exp_f32_e32 v72, v72
	v_pk_mul_f32 v[80:81], v[120:121], v[80:81] op_sel_hi:[0,1]
	v_lshlrev_b32_e32 v76, 16, v77
	v_and_b32_e32 v77, 0xffff0000, v77
	v_add_f32_e32 v72, 1.0, v72
	v_rcp_f32_e32 v93, v72
	v_pk_fma_f32 v[80:81], v[80:81], v[98:99], v[84:85]
	v_pk_mul_f32 v[76:77], v[118:119], v[76:77] op_sel_hi:[0,1]
	v_lshlrev_b32_e32 v72, 16, v73
	v_and_b32_e32 v73, 0xffff0000, v73
	v_pk_fma_f32 v[76:77], v[76:77], v[102:103], v[80:81]
	v_pk_mul_f32 v[72:73], v[116:117], v[72:73] op_sel_hi:[0,1]
	v_pk_fma_f32 v[72:73], v[72:73], v[144:145], v[76:77]
	v_pk_mul_f32 v[88:89], v[88:89], v[92:93]
	v_mul_f32_e32 v76, 0xbfb8aa3b, v72
	v_mul_f32_e32 v77, 0xbfb8aa3b, v73
	v_exp_f32_e32 v76, v76
	v_exp_f32_e32 v77, v77
	s_mov_b32 s22, 0x3e000000
	v_pk_mul_f32 v[114:115], v[88:89], s[22:23] op_sel_hi:[1,0]
	v_add_f32_e32 v76, 1.0, v76
	v_add_f32_e32 v77, 1.0, v77
	v_rcp_f32_e32 v76, v76
	v_rcp_f32_e32 v77, v77
	ds_read_b128 v[88:91], v141 offset:9232
	ds_read_b128 v[92:95], v141 offset:1040
	ds_read_b128 v[96:99], v141 offset:3088
	v_pk_mul_f32 v[72:73], v[72:73], v[76:77]
	ds_read_b128 v[100:103], v141 offset:5136
	ds_read_b128 v[142:145], v141 offset:7184
	v_pk_mul_f32 v[84:85], v[72:73], s[22:23] op_sel_hi:[1,0]
	v_lshlrev_b32_e32 v72, 16, v86
	v_and_b32_e32 v73, 0xffff0000, v86
	v_pk_mul_f32 v[72:73], v[122:123], v[72:73] op_sel_hi:[0,1]
	v_lshlrev_b32_e32 v76, 16, v82
	v_and_b32_e32 v77, 0xffff0000, v82
	s_waitcnt lgkmcnt(3)
	v_pk_fma_f32 v[72:73], v[72:73], v[92:93], v[88:89]
	v_pk_mul_f32 v[76:77], v[120:121], v[76:77] op_sel_hi:[0,1]
	s_waitcnt lgkmcnt(2)
	v_pk_fma_f32 v[72:73], v[76:77], v[96:97], v[72:73]
	v_lshlrev_b32_e32 v76, 16, v78
	v_and_b32_e32 v77, 0xffff0000, v78
	v_pk_mul_f32 v[76:77], v[118:119], v[76:77] op_sel_hi:[0,1]
	s_waitcnt lgkmcnt(1)
	v_pk_fma_f32 v[72:73], v[76:77], v[100:101], v[72:73]
	v_lshlrev_b32_e32 v76, 16, v74
	v_and_b32_e32 v77, 0xffff0000, v74
	v_pk_mul_f32 v[76:77], v[116:117], v[76:77] op_sel_hi:[0,1]
	s_waitcnt lgkmcnt(0)
; #define LAS __attribute__((address_space(3)))
; __device__ __forceinline__ unsigned f2bf(float f) { unsigned u = __builtin_bit_cast(unsigned, f); return (u + 0x7fffu + ((u >> 16) & 1u)) >> 16; }
; __device__ __forceinline__ void unpack8(const v4u r, float* x) { x[0] = bflo(r.x); x[1] = bfhi(r.x); x[2] = bflo(r.y); x[3] = bfhi(r.y); x[4] = bflo(r.z); x[5] = bfhi(r.z); x[6] = bflo(r.w); x[7] = bfhi(r.w); }
; __device__ __forceinline__ v4u pack8(const float* x) { v4u o; o.x = pk2(x[0], x[1]); o.y = pk2(x[2], x[3]); o.z = pk2(x[4], x[5]); o.w = pk2(x[6], x[7]); return o; }
; #define LBAR() do { asm volatile("s_waitcnt lgkmcnt(0)" ::: "memory"); __builtin_amdgcn_s_barrier(); asm volatile("" ::: "memory"); } while (0)
; __device__ __forceinline__ void m3_compute(const M3In& I, const float* mnorm, u16* YB, LAS unsigned char* lds, int un, int tid) {
;     ...
;     { float q[8], k[8], v[8];
;         conv8r(I.q, cwL, h * 64 + dg * 8, q, c * 64 + s);
;         conv8r(I.k, cwL, 256 + h * 64 + dg * 8, k, c * 64 + s);
; #pragma unroll
;         for (int i = 0; i < 8; ++i) k[i] *= 0.125f;
;         unpack8(I.v, v);
;         *(LAS v4u*)(Qs + s * LP + dg * 8) = pack8(q);
;         *(LAS v4u*)(Ks + s * LP + dg * 8) = pack8(k);
; #pragma unroll
;         for (int i = 0; i < 8; ++i) Vt[(dg * 8 + i) * LP + s] = (u16)f2bf(v[i]);
;         *(LAS v4u*)(Cs + s * LP + dg * 8) = I.c; }
;     LBAR();
	v_pk_fma_f32 v[72:73], v[76:77], v[142:143], v[72:73]
	s_nop 0
	v_mul_f32_e32 v74, 0xbfb8aa3b, v72
	v_exp_f32_e32 v74, v74
	s_nop 0
	v_add_f32_e32 v74, 1.0, v74
	v_rcp_f32_e32 v76, v74
	v_mul_f32_e32 v74, 0xbfb8aa3b, v73
	v_exp_f32_e32 v74, v74
	s_nop 0
	v_add_f32_e32 v74, 1.0, v74
	v_rcp_f32_e32 v77, v74
	v_lshlrev_b32_e32 v74, 16, v75
	v_and_b32_e32 v75, 0xffff0000, v75
	v_pk_mul_f32 v[74:75], v[116:117], v[74:75] op_sel_hi:[0,1]
	v_pk_mul_f32 v[72:73], v[72:73], v[76:77]
	v_lshlrev_b32_e32 v76, 16, v83
	v_pk_mul_f32 v[88:89], v[72:73], s[22:23] op_sel_hi:[1,0]
	v_lshlrev_b32_e32 v72, 16, v87
	v_and_b32_e32 v73, 0xffff0000, v87
	v_pk_mul_f32 v[72:73], v[122:123], v[72:73] op_sel_hi:[0,1]
	v_and_b32_e32 v77, 0xffff0000, v83
	v_pk_fma_f32 v[72:73], v[72:73], v[94:95], v[90:91]
	v_pk_mul_f32 v[76:77], v[120:121], v[76:77] op_sel_hi:[0,1]
	v_pk_fma_f32 v[72:73], v[76:77], v[98:99], v[72:73]
	v_lshlrev_b32_e32 v76, 16, v79
	v_and_b32_e32 v77, 0xffff0000, v79
	v_pk_mul_f32 v[76:77], v[118:119], v[76:77] op_sel_hi:[0,1]
	v_pk_fma_f32 v[72:73], v[76:77], v[102:103], v[72:73]
	ds_read_b128 v[76:79], v141 offset:8192
	v_pk_fma_f32 v[72:73], v[74:75], v[144:145], v[72:73]
	v_lshlrev_b32_e32 v90, 16, v68
	v_mul_f32_e32 v74, 0xbfb8aa3b, v72
	v_mul_f32_e32 v75, 0xbfb8aa3b, v73
	v_exp_f32_e32 v74, v74
	v_exp_f32_e32 v75, v75
	v_and_b32_e32 v91, 0xffff0000, v68
	v_pk_mul_f32 v[90:91], v[122:123], v[90:91] op_sel_hi:[0,1]
	v_add_f32_e32 v74, 1.0, v74
	v_add_f32_e32 v75, 1.0, v75
	v_rcp_f32_e32 v74, v74
	v_rcp_f32_e32 v75, v75
	v_lshlrev_b32_e32 v68, 16, v69
	v_and_b32_e32 v69, 0xffff0000, v69
	v_pk_mul_f32 v[68:69], v[122:123], v[68:69] op_sel_hi:[0,1]
	v_pk_mul_f32 v[72:73], v[72:73], v[74:75]
	s_nop 0
	v_pk_mul_f32 v[86:87], v[72:73], s[22:23] op_sel_hi:[1,0]
	ds_read_b128 v[80:83], v141
	ds_read_b128 v[72:75], v141 offset:16
	ds_read_b128 v[94:97], v141 offset:4096
	ds_read_b128 v[98:101], v141 offset:6144
	s_waitcnt lgkmcnt(3)
	v_pk_fma_f32 v[76:77], v[90:91], v[80:81], v[76:77]
	ds_read_b128 v[90:93], v141 offset:2048
	v_lshlrev_b32_e32 v80, 16, v64
	v_and_b32_e32 v81, 0xffff0000, v64
	v_pk_mul_f32 v[80:81], v[120:121], v[80:81] op_sel_hi:[0,1]
	v_lshlrev_b32_e32 v64, 16, v65
	s_waitcnt lgkmcnt(0)
	v_pk_fma_f32 v[76:77], v[80:81], v[90:91], v[76:77]
	v_lshlrev_b32_e32 v80, 16, v60
	v_and_b32_e32 v81, 0xffff0000, v60
	v_pk_mul_f32 v[80:81], v[118:119], v[80:81] op_sel_hi:[0,1]
	v_pk_fma_f32 v[76:77], v[80:81], v[94:95], v[76:77]
	v_lshlrev_b32_e32 v80, 16, v56
	v_and_b32_e32 v81, 0xffff0000, v56
	v_pk_mul_f32 v[80:81], v[116:117], v[80:81] op_sel_hi:[0,1]
	v_pk_fma_f32 v[76:77], v[80:81], v[98:99], v[76:77]
	v_and_b32_e32 v65, 0xffff0000, v65
	v_mul_f32_e32 v56, 0xbfb8aa3b, v76
	v_exp_f32_e32 v56, v56
	v_pk_fma_f32 v[68:69], v[68:69], v[82:83], v[78:79]
	v_pk_mul_f32 v[64:65], v[120:121], v[64:65] op_sel_hi:[0,1]
	v_lshlrev_b32_e32 v60, 16, v61
	v_add_f32_e32 v56, 1.0, v56
	v_rcp_f32_e32 v80, v56
	v_mul_f32_e32 v56, 0xbfb8aa3b, v77
	v_exp_f32_e32 v56, v56
	v_and_b32_e32 v61, 0xffff0000, v61
	v_pk_fma_f32 v[64:65], v[64:65], v[92:93], v[68:69]
	v_pk_mul_f32 v[60:61], v[118:119], v[60:61] op_sel_hi:[0,1]
	v_add_f32_e32 v56, 1.0, v56
	v_rcp_f32_e32 v81, v56
	v_lshlrev_b32_e32 v56, 16, v57
	v_and_b32_e32 v57, 0xffff0000, v57
	v_pk_fma_f32 v[60:61], v[60:61], v[96:97], v[64:65]
	v_pk_mul_f32 v[56:57], v[116:117], v[56:57] op_sel_hi:[0,1]
	v_pk_fma_f32 v[56:57], v[56:57], v[100:101], v[60:61]
	v_pk_mul_f32 v[90:91], v[76:77], v[80:81]
	v_mul_f32_e32 v60, 0xbfb8aa3b, v56
	v_mul_f32_e32 v61, 0xbfb8aa3b, v57
	v_exp_f32_e32 v60, v60
	v_exp_f32_e32 v61, v61
	ds_read_b128 v[76:79], v141 offset:8208
	ds_read_b128 v[96:99], v141 offset:6160
	v_add_f32_e32 v60, 1.0, v60
	v_add_f32_e32 v61, 1.0, v61
	v_rcp_f32_e32 v60, v60
	v_rcp_f32_e32 v61, v61
	ds_read_b128 v[80:83], v141 offset:2064
	ds_read_b128 v[92:95], v141 offset:4112
	v_lshlrev_b32_e32 v64, 16, v66
	v_pk_mul_f32 v[56:57], v[56:57], v[60:61]
	v_lshlrev_b32_e32 v60, 16, v70
	v_and_b32_e32 v61, 0xffff0000, v70
	v_pk_mul_f32 v[60:61], v[122:123], v[60:61] op_sel_hi:[0,1]
	v_and_b32_e32 v65, 0xffff0000, v66
	s_waitcnt lgkmcnt(3)
	v_pk_fma_f32 v[60:61], v[60:61], v[72:73], v[76:77]
	v_pk_mul_f32 v[64:65], v[120:121], v[64:65] op_sel_hi:[0,1]
	s_waitcnt lgkmcnt(1)
	v_pk_fma_f32 v[60:61], v[64:65], v[80:81], v[60:61]
	v_lshlrev_b32_e32 v64, 16, v62
	v_and_b32_e32 v65, 0xffff0000, v62
	v_pk_mul_f32 v[64:65], v[118:119], v[64:65] op_sel_hi:[0,1]
	s_waitcnt lgkmcnt(0)
	v_pk_fma_f32 v[60:61], v[64:65], v[92:93], v[60:61]
	v_lshlrev_b32_e32 v64, 16, v58
	v_and_b32_e32 v65, 0xffff0000, v58
	v_pk_mul_f32 v[64:65], v[116:117], v[64:65] op_sel_hi:[0,1]
	v_pk_fma_f32 v[60:61], v[64:65], v[96:97], v[60:61]
	v_lshlrev_b32_e32 v66, 16, v67
	v_mul_f32_e32 v58, 0xbfb8aa3b, v60
	v_exp_f32_e32 v58, v58
	v_and_b32_e32 v67, 0xffff0000, v67
	v_pk_mul_f32 v[66:67], v[120:121], v[66:67] op_sel_hi:[0,1]
	v_lshlrev_b32_e32 v62, 16, v63
	v_add_f32_e32 v58, 1.0, v58
	v_rcp_f32_e32 v64, v58
	v_mul_f32_e32 v58, 0xbfb8aa3b, v61
	v_exp_f32_e32 v58, v58
	v_and_b32_e32 v63, 0xffff0000, v63
	v_pk_mul_f32 v[62:63], v[118:119], v[62:63] op_sel_hi:[0,1]
	v_add_f32_e32 v58, 1.0, v58
	v_rcp_f32_e32 v65, v58
	v_lshlrev_b32_e32 v58, 16, v59
	v_and_b32_e32 v59, 0xffff0000, v59
	v_pk_mul_f32 v[58:59], v[116:117], v[58:59] op_sel_hi:[0,1]
	v_pk_mul_f32 v[60:61], v[60:61], v[64:65]
	v_lshlrev_b32_e32 v64, 16, v71
	v_and_b32_e32 v65, 0xffff0000, v71
	v_pk_mul_f32 v[64:65], v[122:123], v[64:65] op_sel_hi:[0,1]
	v_pk_fma_f32 v[64:65], v[64:65], v[74:75], v[78:79]
	v_cvt_pk_bf16_f32 v60, v60, v61
	v_pk_fma_f32 v[64:65], v[66:67], v[82:83], v[64:65]
	s_nop 0
	v_pk_fma_f32 v[62:63], v[62:63], v[94:95], v[64:65]
	s_nop 0
	v_pk_fma_f32 v[58:59], v[58:59], v[98:99], v[62:63]
	s_nop 0
	v_mul_f32_e32 v62, 0xbfb8aa3b, v58
	v_mul_f32_e32 v63, 0xbfb8aa3b, v59
	v_exp_f32_e32 v62, v62
	v_exp_f32_e32 v63, v63
	v_add_f32_e32 v62, 1.0, v62
	v_add_f32_e32 v63, 1.0, v63
	v_rcp_f32_e32 v62, v62
	v_rcp_f32_e32 v63, v63
	s_nop 0
	v_pk_mul_f32 v[62:63], v[58:59], v[62:63]
	v_cvt_pk_bf16_f32 v58, v90, v91
	v_cvt_pk_bf16_f32 v59, v56, v57
	v_cvt_pk_bf16_f32 v61, v62, v63
	ds_write_b128 v121, v[58:61] offset:2048
	v_cvt_pk_bf16_f32 v56, v114, v115
	v_cvt_pk_bf16_f32 v57, v84, v85
	v_cvt_pk_bf16_f32 v58, v88, v89
	v_cvt_pk_bf16_f32 v59, v86, v87
	ds_write_b128 v121, v[56:59] offset:11264
	ds_write_b16 v111, v48 offset:20480
	ds_write_b16_d16_hi v111, v48 offset:20624
	ds_write_b16 v111, v49 offset:20768
	ds_write_b16_d16_hi v111, v49 offset:20912
	ds_write_b16 v111, v50 offset:21056
	ds_write_b16_d16_hi v111, v50 offset:21200
	ds_write_b16 v111, v51 offset:21344
	ds_write_b16_d16_hi v111, v51 offset:21488
	ds_write_b128 v121, v[52:55] offset:29696
	s_waitcnt lgkmcnt(0)
	s_barrier
; __device__ __forceinline__ void m3_compute(const M3In& I, const float* mnorm, u16* YB, LAS unsigned char* lds, int un, int tid) {
;     ...
;     const int tr = wave >> 1, tc0 = (wave & 1) * 2, fr = lane & 15, fq = lane >> 4;
;     {
;         v4f a0 = {0.f, 0.f, 0.f, 0.f}, a1 = {0.f, 0.f, 0.f, 0.f};
; #pragma unroll
;         for (int kk = 0; kk < 2; ++kk) { const v8s a = lds_frag(Qs, 16 * tr + fr, 32 * kk + 8 * fq);
;             a0 = __builtin_amdgcn_mfma_f32_16x16x32_bf16(a, lds_frag(Ks, 16 * tc0 + fr, 32 * kk + 8 * fq), a0, 0, 0, 0);
;             a1 = __builtin_amdgcn_mfma_f32_16x16x32_bf16(a, lds_frag(Ks, 16 * tc0 + 16 + fr, 32 * kk + 8 * fq), a1, 0, 0, 0); }
; #pragma unroll
;         for (int rg = 0; rg < 4; ++rg) { const int t = 16 * tr + 4 * fq + rg; const float mt = Mx[t];
;             const int s0 = 16 * tc0 + fr, s1 = s0 + 16;
;             const float w0 = s0 <= t ? __expf(av[s0] - mt) : 0.f, w1 = s1 <= t ? __expf(av[s1] - mt) : 0.f;
	ds_read_b128 v[48:51], v123 offset:2048
	ds_read_b128 v[52:55], v124 offset:11264
	ds_read_b128 v[56:59], v124 offset:13568
	s_waitcnt lgkmcnt(1)
	v_mfma_f32_16x16x32_bf16 v[52:55], v[48:51], v[52:55], 0
	s_waitcnt lgkmcnt(0)
	v_mfma_f32_16x16x32_bf16 v[56:59], v[48:51], v[56:59], 0
	ds_read_b128 v[60:63], v123 offset:2112
	ds_read_b128 v[48:51], v124 offset:11328
	s_waitcnt lgkmcnt(0)
	v_mfma_f32_16x16x32_bf16 v[48:51], v[60:63], v[48:51], v[52:55]
	s_nop 2
	ds_read_b128 v[52:55], v124 offset:13632
	s_waitcnt lgkmcnt(0)
	v_mfma_f32_16x16x32_bf16 v[52:55], v[60:63], v[52:55], v[56:59]
	s_nop 2
	ds_read_b32 v57, v126 offset:256
	v_mov_b32_e32 v56, 0
	v_mov_b32_e32 v58, 0
	s_and_saveexec_b64 s[22:23], s[4:5]
	s_cbranch_execz .LBB0_962
	ds_read_b32 v58, v125
	s_waitcnt lgkmcnt(0)
	v_sub_f32_e32 v58, v58, v57
	v_mul_f32_e32 v58, 0x3fb8aa3b, v58
	v_exp_f32_e32 v58, v58

; __device__ __forceinline__ void attn_post(const u16* O, u16* YC, const float* dlam, const float* dnorm, float lambda_init, int gt, int nthreads, int lane) {
;     ...
;     for (int item0 = gt >> 4; item0 < MH * 4; item0 += 8 * stride) {
;         v4u ra[8], rb[8];
; #pragma unroll
;         for (int q = 0; q < 8; ++q) { const int item = item0 + q * stride < MH * 4 ? item0 + q * stride : item0; const int row = item >> 2, hh = item & 3;
;             ra[q] = *(const v4u*)(O + (size_t)row * 1024 + (2 * hh) * 128 + sub * 8); rb[q] = *(const v4u*)(O + (size_t)row * 1024 + (2 * hh + 1) * 128 + sub * 8); }
; #pragma unroll
.LBB0_982:
	v_ashrrev_i32_e32 v0, 2, v62
	v_ashrrev_i32_e32 v1, 31, v0
	v_lshlrev_b64 v[0:1], 11, v[0:1]
	v_and_b32_e32 v2, 0x300, v73
	v_lshl_add_u64 v[0:1], s[16:17], 0, v[0:1]
	v_lshlrev_b32_e32 v220, 1, v2
	v_lshl_add_u64 v[0:1], v[0:1], 0, v[220:221]
	v_lshlrev_b32_e32 v220, 1, v48
	v_lshl_add_u64 v[0:1], v[0:1], 0, v[220:221]
	v_mov_b64_e32 v[64:65], v[146:147]
	v_mov_b64_e32 v[66:67], v[148:149]
	v_mov_b64_e32 v[82:83], v[150:151]
	v_mov_b64_e32 v[84:85], v[152:153]
	v_add_u32_e32 v74, s22, v62
	v_cmp_gt_i32_e64 s[0:1], s81, v74
	v_mov_b32_e32 v3, v221
	v_add_u32_e32 v81, s30, v62
	v_cndmask_b32_e64 v2, v62, v74, s[0:1]
	v_ashrrev_i32_e32 v0, 2, v2
	v_ashrrev_i32_e32 v1, 31, v0
	v_lshlrev_b64 v[0:1], 11, v[0:1]
	v_lshlrev_b32_e32 v2, 9, v2
	v_lshl_add_u64 v[0:1], s[16:17], 0, v[0:1]
	v_and_b32_e32 v2, 0x600, v2
	v_lshl_add_u64 v[0:1], v[0:1], 0, v[2:3]
	v_cmp_gt_i32_e64 s[10:11], s81, v81
	v_lshl_add_u64 v[0:1], v[0:1], 0, v[220:221]
	v_mov_b64_e32 v[86:87], v[154:155]
	v_mov_b64_e32 v[88:89], v[156:157]
	v_mov_b64_e32 v[90:91], v[158:159]
	v_mov_b64_e32 v[92:93], v[160:161]
	v_cndmask_b32_e64 v2, v62, v81, s[10:11]
	v_ashrrev_i32_e32 v0, 2, v2
	v_ashrrev_i32_e32 v1, 31, v0
	v_lshlrev_b64 v[0:1], 11, v[0:1]
	v_lshlrev_b32_e32 v2, 9, v2
	s_mul_i32 s2, s60, 0x60
	v_lshl_add_u64 v[0:1], s[16:17], 0, v[0:1]
	v_and_b32_e32 v2, 0x600, v2
	v_add_u32_e32 v80, s2, v62
	v_lshl_add_u64 v[0:1], v[0:1], 0, v[2:3]
	v_cmp_gt_i32_e64 s[8:9], s81, v80
	v_lshl_add_u64 v[0:1], v[0:1], 0, v[220:221]
	v_mov_b64_e32 v[44:45], v[162:163]
	v_mov_b64_e32 v[46:47], v[164:165]
	v_mov_b64_e32 v[40:41], v[166:167]
	v_mov_b64_e32 v[42:43], v[168:169]
	v_cndmask_b32_e64 v2, v62, v80, s[8:9]
	v_ashrrev_i32_e32 v0, 2, v2
	v_ashrrev_i32_e32 v1, 31, v0
	v_lshlrev_b64 v[0:1], 11, v[0:1]
	v_lshlrev_b32_e32 v2, 9, v2
	v_lshl_add_u64 v[0:1], s[16:17], 0, v[0:1]
	v_and_b32_e32 v2, 0x600, v2
	v_add_u32_e32 v79, s37, v62
	v_lshl_add_u64 v[0:1], v[0:1], 0, v[2:3]
	v_cmp_gt_i32_e64 s[6:7], s81, v79
	v_lshl_add_u64 v[0:1], v[0:1], 0, v[220:221]
	v_mov_b64_e32 v[36:37], v[170:171]
	v_mov_b64_e32 v[38:39], v[172:173]
	v_mov_b64_e32 v[32:33], v[174:175]
	v_mov_b64_e32 v[34:35], v[176:177]
	v_cndmask_b32_e64 v2, v62, v79, s[6:7]
	v_ashrrev_i32_e32 v0, 2, v2
	v_ashrrev_i32_e32 v1, 31, v0
	v_lshlrev_b64 v[0:1], 11, v[0:1]
	v_lshlrev_b32_e32 v2, 9, v2
	s_mul_i32 s2, s60, 0xa0
	v_lshl_add_u64 v[0:1], s[16:17], 0, v[0:1]
	v_and_b32_e32 v2, 0x600, v2
	v_add_u32_e32 v78, s2, v62
	v_lshl_add_u64 v[0:1], v[0:1], 0, v[2:3]
	v_cmp_gt_i32_e64 s[4:5], s81, v78
	v_lshl_add_u64 v[0:1], v[0:1], 0, v[220:221]
	v_mov_b64_e32 v[28:29], v[178:179]
	v_mov_b64_e32 v[30:31], v[180:181]
	v_mov_b64_e32 v[24:25], v[182:183]
	v_mov_b64_e32 v[26:27], v[184:185]
	v_cndmask_b32_e64 v2, v62, v78, s[4:5]
	v_ashrrev_i32_e32 v0, 2, v2
	v_ashrrev_i32_e32 v1, 31, v0
	v_lshlrev_b64 v[0:1], 11, v[0:1]
	v_lshlrev_b32_e32 v2, 9, v2
	s_mul_i32 s2, s60, 0xc0
	v_lshl_add_u64 v[0:1], s[16:17], 0, v[0:1]
	v_and_b32_e32 v2, 0x600, v2
	v_add_u32_e32 v76, s2, v62
	v_lshl_add_u64 v[0:1], v[0:1], 0, v[2:3]
	v_cmp_gt_i32_e64 s[2:3], s81, v76
	v_lshl_add_u64 v[0:1], v[0:1], 0, v[220:221]
	v_mov_b64_e32 v[20:21], v[186:187]
	v_mov_b64_e32 v[22:23], v[188:189]
	v_mov_b64_e32 v[16:17], v[190:191]
	v_mov_b64_e32 v[18:19], v[192:193]
	v_cndmask_b32_e64 v2, v62, v76, s[2:3]
	v_ashrrev_i32_e32 v0, 2, v2
	v_ashrrev_i32_e32 v1, 31, v0
	v_lshlrev_b64 v[0:1], 11, v[0:1]
	v_lshlrev_b32_e32 v2, 9, v2
	s_mul_i32 s12, s60, 0xe0
	v_lshl_add_u64 v[0:1], s[16:17], 0, v[0:1]
	v_and_b32_e32 v2, 0x600, v2
	v_add_u32_e32 v75, s12, v62
	v_lshl_add_u64 v[0:1], v[0:1], 0, v[2:3]
	v_cmp_gt_i32_e32 vcc, s81, v75
	v_lshl_add_u64 v[0:1], v[0:1], 0, v[220:221]
	v_mov_b64_e32 v[12:13], v[194:195]
	v_mov_b64_e32 v[14:15], v[196:197]
	v_mov_b64_e32 v[8:9], v[198:199]
	v_mov_b64_e32 v[10:11], v[200:201]
	v_cndmask_b32_e32 v2, v62, v75, vcc
	v_ashrrev_i32_e32 v0, 2, v2
	v_ashrrev_i32_e32 v1, 31, v0
	v_lshlrev_b64 v[0:1], 11, v[0:1]
	v_lshlrev_b32_e32 v2, 9, v2
	v_lshl_add_u64 v[0:1], s[16:17], 0, v[0:1]
	v_and_b32_e32 v2, 0x600, v2
	v_lshl_add_u64 v[0:1], v[0:1], 0, v[2:3]
	v_lshl_add_u64 v[0:1], v[0:1], 0, v[220:221]
	v_mov_b64_e32 v[4:5], v[202:203]
	v_mov_b64_e32 v[6:7], v[204:205]
	s_nop 0
	v_mov_b64_e32 v[0:1], v[206:207]
	v_mov_b64_e32 v[2:3], v[208:209]
	s_waitcnt vmcnt(15)
	v_lshlrev_b32_e32 v60, 16, v67
	v_and_b32_e32 v61, 0xffff0000, v67
	v_lshlrev_b32_e32 v94, 16, v66
	v_and_b32_e32 v95, 0xffff0000, v66
	s_waitcnt vmcnt(14)
; __device__ __forceinline__ void unpack8(const v4u r, float* x) { x[0] = bflo(r.x); x[1] = bfhi(r.x); x[2] = bflo(r.y); x[3] = bfhi(r.y); x[4] = bflo(r.z); x[5] = bfhi(r.z); x[6] = bflo(r.w); x[7] = bfhi(r.w); }
; __device__ __forceinline__ v4u pack8(const float* x) { v4u o; o.x = pk2(x[0], x[1]); o.y = pk2(x[2], x[3]); o.z = pk2(x[4], x[5]); o.w = pk2(x[6], x[7]); return o; }
; __device__ __forceinline__ float red16(float v) { v = red8(v); v += dpp_<0x140, 0xF>(0.f, v); return v; }
; __device__ __forceinline__ size_t tl(int row, int col, int K) { return (size_t)(row >> 8) * ((size_t)256 * K) + (size_t)(col >> 6) * (256 * 64) + (size_t)((row & 255) * 64 + (col & 63)); }
; __device__ __forceinline__ void attn_post(const u16* O, u16* YC, const float* dlam, const float* dnorm, float lambda_init, int gt, int nthreads, int lane) {
;     ...
;         for (int q = 0; q < 8; ++q) { const int item = item0 + q * stride; const int row = item >> 2, hh = item & 3; float a[8], b[8], d[8]; float ss = 0.f;
;             unpack8(ra[q], a); unpack8(rb[q], b);
; #pragma unroll
;             for (int i = 0; i < 8; ++i) { d[i] = a[i] - lam * b[i]; ss += d[i] * d[i]; }
;             ss = red16(ss);
;             const float r = rsqrtf(ss * (1.0f / 128.0f) + EPS);
; #pragma unroll
;             for (int i = 0; i < 8; ++i) d[i] *= r * gn[i];
;             if (item < MH * 4) *(v4u*)(YC + (size_t)(hh >> 1) * MH * 256 + tl(row, (hh & 1) * 128 + sub * 8, 256)) = pack8(d); }
	v_lshlrev_b32_e32 v66, 16, v84
	v_and_b32_e32 v67, 0xffff0000, v84
	v_pk_fma_f32 v[66:67], v[58:59], v[66:67], v[94:95] neg_lo:[1,0,0] neg_hi:[1,0,0]
	v_lshlrev_b32_e32 v94, 16, v65
	v_and_b32_e32 v95, 0xffff0000, v65
	v_lshlrev_b32_e32 v98, 16, v64
	v_and_b32_e32 v99, 0xffff0000, v64
	v_lshlrev_b32_e32 v64, 16, v82
	v_and_b32_e32 v65, 0xffff0000, v82
	v_lshlrev_b32_e32 v96, 16, v83
	v_and_b32_e32 v97, 0xffff0000, v83
	v_pk_fma_f32 v[64:65], v[58:59], v[64:65], v[98:99] neg_lo:[1,0,0] neg_hi:[1,0,0]
	v_pk_fma_f32 v[94:95], v[58:59], v[96:97], v[94:95] neg_lo:[1,0,0] neg_hi:[1,0,0]
	v_pk_mul_f32 v[82:83], v[64:65], v[64:65]
	v_pk_mul_f32 v[96:97], v[94:95], v[94:95]
	v_add_f32_e32 v63, v82, v83
	v_add_f32_e32 v63, v96, v63
	v_lshlrev_b32_e32 v68, 16, v85
	v_and_b32_e32 v69, 0xffff0000, v85
	v_pk_mul_f32 v[84:85], v[66:67], v[66:67]
	v_add_f32_e32 v63, v97, v63
	v_pk_fma_f32 v[60:61], v[58:59], v[68:69], v[60:61] neg_lo:[1,0,0] neg_hi:[1,0,0]
	v_add_f32_e32 v63, v84, v63
	v_pk_mul_f32 v[68:69], v[60:61], v[60:61]
	v_add_f32_e32 v63, v85, v63
	v_add_f32_e32 v63, v68, v63
	v_add_f32_e32 v63, v69, v63
	v_ashrrev_i32_e32 v62, 10, v62
	s_nop 0
	v_add_f32_dpp v63, v63, v63 quad_perm:[1,0,3,2] row_mask:0xf bank_mask:0xf bound_ctrl:1
	s_nop 1
	v_add_f32_dpp v63, v63, v63 quad_perm:[2,3,0,1] row_mask:0xf bank_mask:0xf bound_ctrl:1
	s_nop 1
	v_add_f32_dpp v63, v63, v63 row_half_mirror row_mask:0xf bank_mask:0xf bound_ctrl:1
	s_nop 1
	v_add_f32_dpp v63, v63, v63 row_mirror row_mask:0xf bank_mask:0xf bound_ctrl:1
	v_fmamk_f32 v63, v63, 0x3c000000, v235
	v_mul_f32_e32 v68, 0x4b800000, v63
	v_cmp_gt_f32_e64 s[12:13], s25, v63
	s_nop 1
	v_cndmask_b32_e64 v63, v63, v68, s[12:13]
	v_rsq_f32_e32 v63, v63
	s_nop 0
	v_mul_f32_e32 v68, 0x45800000, v63
	v_cndmask_b32_e64 v68, v63, v68, s[12:13]
	v_pk_mul_f32 v[82:83], v[50:51], v[68:69] op_sel_hi:[1,0]
	v_pk_mul_f32 v[84:85], v[54:55], v[68:69] op_sel_hi:[1,0]
	v_pk_mul_f32 v[64:65], v[64:65], v[82:83]
	v_pk_mul_f32 v[82:83], v[52:53], v[68:69] op_sel_hi:[1,0]
	v_pk_mul_f32 v[68:69], v[56:57], v[68:69] op_sel_hi:[1,0]
	v_pk_mul_f32 v[66:67], v[66:67], v[84:85]
	v_pk_mul_f32 v[60:61], v[60:61], v[68:69]
	v_and_or_b32 v68, v71, s90, v48
	v_cvt_pk_bf16_f32 v66, v66, v67
	v_cvt_pk_bf16_f32 v67, v60, v61
	v_and_b32_e32 v60, 0x400000, v72
	v_lshlrev_b32_e32 v68, 8, v68
	v_lshlrev_b32_e32 v220, 1, v60
	v_ashrrev_i32_e32 v63, 31, v62
	v_and_b32_e32 v77, 0xc000, v68
	v_and_b32_e32 v68, 0x3fc0, v70
	v_lshl_add_u64 v[60:61], s[18:19], 0, v[220:221]
	v_or3_b32 v68, v49, v68, v77
	v_lshlrev_b64 v[62:63], 17, v[62:63]
	v_pk_mul_f32 v[82:83], v[94:95], v[82:83]
	v_lshl_add_u64 v[62:63], v[60:61], 0, v[62:63]
	v_lshlrev_b32_e32 v220, 1, v68
	v_cvt_pk_bf16_f32 v64, v64, v65
	v_cvt_pk_bf16_f32 v65, v82, v83
	v_lshl_add_u64 v[62:63], v[62:63], 0, v[220:221]
	global_store_dwordx4 v[62:63], v[64:67], off
	s_waitcnt vmcnt(14)
	v_lshlrev_b32_e32 v62, 16, v86
	v_and_b32_e32 v63, 0xffff0000, v86
	s_waitcnt vmcnt(13)
	v_lshlrev_b32_e32 v64, 16, v90
	v_and_b32_e32 v65, 0xffff0000, v90
	v_pk_fma_f32 v[62:63], v[58:59], v[64:65], v[62:63] neg_lo:[1,0,0] neg_hi:[1,0,0]
	v_lshlrev_b32_e32 v64, 16, v87
	v_and_b32_e32 v65, 0xffff0000, v87
	v_lshlrev_b32_e32 v66, 16, v91
	v_and_b32_e32 v67, 0xffff0000, v91
	v_pk_mul_f32 v[82:83], v[62:63], v[62:63]
	v_pk_fma_f32 v[64:65], v[58:59], v[66:67], v[64:65] neg_lo:[1,0,0] neg_hi:[1,0,0]
	v_lshlrev_b32_e32 v66, 16, v88
	v_pk_mul_f32 v[84:85], v[64:65], v[64:65]
	v_and_b32_e32 v67, 0xffff0000, v88
	v_lshlrev_b32_e32 v68, 16, v92
	v_and_b32_e32 v69, 0xffff0000, v92
	v_add_f32_e32 v82, v82, v83
	v_pk_fma_f32 v[66:67], v[58:59], v[68:69], v[66:67] neg_lo:[1,0,0] neg_hi:[1,0,0]
	v_add_f32_e32 v82, v84, v82
	v_pk_mul_f32 v[86:87], v[66:67], v[66:67]
	v_lshlrev_b32_e32 v68, 16, v89
	v_and_b32_e32 v69, 0xffff0000, v89
	v_lshlrev_b32_e32 v88, 16, v93
	v_and_b32_e32 v89, 0xffff0000, v93
	v_add_f32_e32 v82, v85, v82
	v_pk_fma_f32 v[68:69], v[58:59], v[88:89], v[68:69] neg_lo:[1,0,0] neg_hi:[1,0,0]
	v_add_f32_e32 v82, v86, v82
	v_pk_mul_f32 v[88:89], v[68:69], v[68:69]
	v_add_f32_e32 v82, v87, v82
	v_add_f32_e32 v82, v88, v82
	v_add_f32_e32 v82, v89, v82
	v_mov_b32_e32 v83, v221
	s_nop 0
	v_add_f32_dpp v82, v82, v82 quad_perm:[1,0,3,2] row_mask:0xf bank_mask:0xf bound_ctrl:1
	s_nop 1
	v_add_f32_dpp v82, v82, v82 quad_perm:[2,3,0,1] row_mask:0xf bank_mask:0xf bound_ctrl:1
	s_nop 1
	v_add_f32_dpp v82, v82, v82 row_half_mirror row_mask:0xf bank_mask:0xf bound_ctrl:1
	s_nop 1
	v_mov_b32_dpp v83, v82 row_mirror row_mask:0xf bank_mask:0xf
	s_and_saveexec_b64 s[12:13], s[0:1]
	s_cbranch_execz .LBB0_984
	v_add_f32_e32 v82, v82, v83
	v_fmamk_f32 v82, v82, 0x3c000000, v235
	v_cmp_gt_f32_e64 s[0:1], s25, v82
	v_mul_f32_e32 v83, 0x4b800000, v82
	s_nop 0
	v_cndmask_b32_e64 v82, v82, v83, s[0:1]
	v_rsq_f32_e32 v82, v82
	s_nop 0
	v_mul_f32_e32 v83, 0x45800000, v82
	v_cndmask_b32_e64 v82, v82, v83, s[0:1]
	v_pk_mul_f32 v[84:85], v[50:51], v[82:83] op_sel_hi:[1,0]
	s_nop 0
	v_pk_mul_f32 v[62:63], v[62:63], v[84:85]
	v_pk_mul_f32 v[84:85], v[52:53], v[82:83] op_sel_hi:[1,0]
	v_cvt_pk_bf16_f32 v62, v62, v63
	v_pk_mul_f32 v[64:65], v[64:65], v[84:85]
	v_pk_mul_f32 v[84:85], v[54:55], v[82:83] op_sel_hi:[1,0]
	v_pk_mul_f32 v[82:83], v[56:57], v[82:83] op_sel_hi:[1,0]
	v_pk_mul_f32 v[66:67], v[66:67], v[84:85]
	v_pk_mul_f32 v[68:69], v[68:69], v[82:83]
	v_cvt_pk_bf16_f32 v63, v64, v65
	v_cvt_pk_bf16_f32 v64, v66, v67
	v_cvt_pk_bf16_f32 v65, v68, v69
	v_ashrrev_i32_e32 v66, 10, v74
	v_add_u32_e32 v68, s40, v70
	v_ashrrev_i32_e32 v67, 31, v66
	v_and_b32_e32 v68, 0x3fc0, v68
	v_or3_b32 v68, v68, v77, v49
	v_lshlrev_b64 v[66:67], 17, v[66:67]
	v_lshl_add_u64 v[66:67], v[60:61], 0, v[66:67]
	v_lshlrev_b32_e32 v220, 1, v68
	v_lshl_add_u64 v[66:67], v[66:67], 0, v[220:221]
	global_store_dwordx4 v[66:67], v[62:65], off
